# phase headers after fused epilogues: PART2 loads of all row panels issued before the first reduce (one exposed load latency per header instead of one per panel)
# speedup vs baseline: 1.0006x; 1.0006x over previous
; #define LAS __attribute__((address_space(3)))
; __device__ __forceinline__ void rs_table_fill(LAS unsigned char* lds, const pg8::StaticOrder& S, const float* rs) {
;     int k0 = -1, k1 = -1, k2 = -1, k3 = -1;
;     for (int i = 0;; ++i) { pg8::Unit u; if (!S.next(i, u)) break; const int pm = u.pm;
;         if (pm != k0 && pm != k1 && pm != k2 && pm != k3) { if (k0 < 0) k0 = pm; else if (k1 < 0) k1 = pm; else if (k2 < 0) k2 = pm; else if (k3 < 0) k3 = pm; } }
;     const int tid = threadIdx.x;
;     LAS float* tab = (LAS float*)(lds + RS_TAB_OFF); LAS int* keys = (LAS int*)(lds + RS_KEY_OFF);
;     if (tid < 256) {
;         if (k0 >= 0) tab[tid] = rs[k0 * 256 + tid];
;         if (k1 >= 0) tab[256 + tid] = rs[k1 * 256 + tid];
;         if (k2 >= 0) tab[512 + tid] = rs[k2 * 256 + tid];
;         if (k3 >= 0) tab[768 + tid] = rs[k3 * 256 + tid];
;     }
;     if (tid == 0) { keys[0] = k0; keys[1] = k1; keys[2] = k2; keys[3] = k3; }
;     __syncthreads();
; }
; template <bool SRC_F32, bool FINAL, int R> __device__ __forceinline__ void ew_compute(const EwSet<SRC_F32, R>& S, int rb, const f32x4 (&g)[4], bf16* hb_out, float* out32, float scale, float* rs_out, int lane) {
;     ...
;         if (!FINAL) { const float tot = wave_sum(s2); if (lane == 0) rs_out[rb + i] = 1.0f / sqrtf(tot * (1.f / D) + EPS); }
.LBB0_494:
	s_movk_i32 s0, 0x100
	v_cmp_gt_u32_e32 vcc, s0, v195
	s_and_saveexec_b64 s[0:1], vcc
	s_cbranch_execz .LBB0_503
	s_add_u32 s80, s28, 0x4c00000
	s_addc_u32 s81, s29, 0
	s_cmp_lt_i32 s14, 0
	s_cbranch_scc1 .Lhp0_l0
	v_lshl_or_b32 v0, s14, 8, v195
	v_lshlrev_b32_e32 v2, 6, v0
	global_load_dwordx4 v[4:7], v2, s[80:81]
	global_load_dwordx4 v[8:11], v2, s[80:81] offset:16
	global_load_dwordx4 v[12:15], v2, s[80:81] offset:32
	global_load_dwordx4 v[16:19], v2, s[80:81] offset:48
.Lhp0_l0:
	s_cmp_lt_i32 s15, 0
	s_cbranch_scc1 .Lhp0_l1
	v_lshl_or_b32 v0, s15, 8, v195
	v_lshlrev_b32_e32 v2, 6, v0
	global_load_dwordx4 v[20:23], v2, s[80:81]
	global_load_dwordx4 v[24:27], v2, s[80:81] offset:16
	global_load_dwordx4 v[28:31], v2, s[80:81] offset:32
	global_load_dwordx4 v[32:35], v2, s[80:81] offset:48
.Lhp0_l1:
	s_cmp_lt_i32 s8, 0
	s_cbranch_scc1 .Lhp0_l2
	v_lshl_or_b32 v0, s8, 8, v195
	v_lshlrev_b32_e32 v2, 6, v0
	global_load_dwordx4 v[36:39], v2, s[80:81]
	global_load_dwordx4 v[40:43], v2, s[80:81] offset:16
	global_load_dwordx4 v[44:47], v2, s[80:81] offset:32
	global_load_dwordx4 v[48:51], v2, s[80:81] offset:48
.Lhp0_l2:
	s_cmp_lt_i32 s6, 0
	s_cbranch_scc1 .Lhp0_l3
	v_lshl_or_b32 v0, s6, 8, v195
	v_lshlrev_b32_e32 v2, 6, v0
	global_load_dwordx4 v[52:55], v2, s[80:81]
	global_load_dwordx4 v[56:59], v2, s[80:81] offset:16
	global_load_dwordx4 v[60:63], v2, s[80:81] offset:32
	global_load_dwordx4 v[64:67], v2, s[80:81] offset:48
.Lhp0_l3:
	s_waitcnt vmcnt(0)
	s_cmp_lt_i32 s14, 0
	s_cbranch_scc1 .Lhp0_c0
	v_lshl_or_b32 v0, s14, 8, v195
	v_lshlrev_b32_e32 v3, 2, v0
	v_lshl_add_u32 v1, v195, 2, 0
	v_add_u32_e32 v1, 0x20000, v1
	v_add_f32_e32 v0, v4, v5
	v_add_f32_e32 v0, v6, v0
	v_add_f32_e32 v0, v7, v0
	v_add_f32_e32 v0, v8, v0
	v_add_f32_e32 v0, v9, v0
	v_add_f32_e32 v0, v10, v0
	v_add_f32_e32 v0, v11, v0
	v_add_f32_e32 v0, v12, v0
	v_add_f32_e32 v0, v13, v0
	v_add_f32_e32 v0, v14, v0
	v_add_f32_e32 v0, v15, v0
	v_add_f32_e32 v0, v16, v0
	v_add_f32_e32 v0, v17, v0
	v_add_f32_e32 v0, v18, v0
	v_add_f32_e32 v0, v19, v0
	v_mul_f32_e32 v0, 0x3a800000, v0
	v_add_f32_e32 v0, 0x358637bd, v0
	v_rsq_f32_e32 v0, v0
	s_nop 0
	global_store_dword v3, v0, s[92:93]
	ds_write_b32 v1, v0
.Lhp0_c0:
	s_cmp_lt_i32 s15, 0
	s_cbranch_scc1 .Lhp0_c1
	v_lshl_or_b32 v0, s15, 8, v195
	v_lshlrev_b32_e32 v3, 2, v0
	s_add_i32 s4, 0, 0x20000
	v_lshl_add_u32 v1, v195, 2, 0
	v_add_u32_e32 v1, 0x20000, v1
	v_add_f32_e32 v0, v20, v21
	v_add_f32_e32 v0, v22, v0
	v_add_f32_e32 v0, v23, v0
	v_add_f32_e32 v0, v24, v0
	v_add_f32_e32 v0, v25, v0
	v_add_f32_e32 v0, v26, v0
	v_add_f32_e32 v0, v27, v0
	v_add_f32_e32 v0, v28, v0
	v_add_f32_e32 v0, v29, v0
	v_add_f32_e32 v0, v30, v0
	v_add_f32_e32 v0, v31, v0
	v_add_f32_e32 v0, v32, v0
	v_add_f32_e32 v0, v33, v0
	v_add_f32_e32 v0, v34, v0
	v_add_f32_e32 v0, v35, v0
	v_mul_f32_e32 v0, 0x3a800000, v0
	v_add_f32_e32 v0, 0x358637bd, v0
	v_rsq_f32_e32 v0, v0
	s_nop 0
	global_store_dword v3, v0, s[92:93]
	ds_write_b32 v1, v0 offset:1024
.Lhp0_c1:
	s_cmp_lt_i32 s8, 0
	s_cbranch_scc1 .Lhp0_c2
	v_lshl_or_b32 v0, s8, 8, v195
	v_lshlrev_b32_e32 v3, 2, v0
	s_add_i32 s4, 0, 0x20000
	v_lshl_add_u32 v1, v195, 2, 0
	v_add_u32_e32 v1, 0x20000, v1
	v_add_f32_e32 v0, v36, v37
	v_add_f32_e32 v0, v38, v0
	v_add_f32_e32 v0, v39, v0
	v_add_f32_e32 v0, v40, v0
	v_add_f32_e32 v0, v41, v0
	v_add_f32_e32 v0, v42, v0
	v_add_f32_e32 v0, v43, v0
	v_add_f32_e32 v0, v44, v0
	v_add_f32_e32 v0, v45, v0
	v_add_f32_e32 v0, v46, v0
	v_add_f32_e32 v0, v47, v0
	v_add_f32_e32 v0, v48, v0
	v_add_f32_e32 v0, v49, v0
	v_add_f32_e32 v0, v50, v0
	v_add_f32_e32 v0, v51, v0
	v_mul_f32_e32 v0, 0x3a800000, v0
	v_add_f32_e32 v0, 0x358637bd, v0
	v_rsq_f32_e32 v0, v0
	s_nop 0
	global_store_dword v3, v0, s[92:93]
	ds_write_b32 v1, v0 offset:2048
.Lhp0_c2:
	s_cmp_lt_i32 s6, 0
	s_cbranch_scc1 .Lhp0_c3
	v_lshl_or_b32 v0, s6, 8, v195
	v_lshlrev_b32_e32 v3, 2, v0
	s_add_i32 s4, 0, 0x20000
	v_lshl_add_u32 v1, v195, 2, 0
	v_add_u32_e32 v1, 0x20000, v1
	v_add_f32_e32 v0, v52, v53
	v_add_f32_e32 v0, v54, v0
	v_add_f32_e32 v0, v55, v0
	v_add_f32_e32 v0, v56, v0
	v_add_f32_e32 v0, v57, v0
	v_add_f32_e32 v0, v58, v0
	v_add_f32_e32 v0, v59, v0
	v_add_f32_e32 v0, v60, v0
	v_add_f32_e32 v0, v61, v0
	v_add_f32_e32 v0, v62, v0
	v_add_f32_e32 v0, v63, v0
	v_add_f32_e32 v0, v64, v0
	v_add_f32_e32 v0, v65, v0
	v_add_f32_e32 v0, v66, v0
	v_add_f32_e32 v0, v67, v0
	v_mul_f32_e32 v0, 0x3a800000, v0
	v_add_f32_e32 v0, 0x358637bd, v0
	v_rsq_f32_e32 v0, v0
	s_nop 0
	global_store_dword v3, v0, s[92:93]
	ds_write_b32 v1, v0 offset:3072
.Lhp0_c3:
.LBB0_503:
	s_or_b64 exec, exec, s[0:1]
	v_cmp_eq_u32_e32 vcc, 0, v195
	s_and_saveexec_b64 s[0:1], vcc
	s_cbranch_execz .LBB0_505
	s_add_i32 s4, 0, 0x21000
	v_mov_b32_e32 v0, s14
	v_mov_b32_e32 v1, s15
	v_mov_b32_e32 v2, s8
	v_mov_b32_e32 v3, s6
	v_mov_b32_e32 v4, s4
	ds_write_b128 v4, v[0:3]

; #define LAS __attribute__((address_space(3)))
; __device__ __forceinline__ void rs_table_fill(LAS unsigned char* lds, const pg8::StaticOrder& S, const float* rs) {
;     int k0 = -1, k1 = -1, k2 = -1, k3 = -1;
;     for (int i = 0;; ++i) { pg8::Unit u; if (!S.next(i, u)) break; const int pm = u.pm;
;         if (pm != k0 && pm != k1 && pm != k2 && pm != k3) { if (k0 < 0) k0 = pm; else if (k1 < 0) k1 = pm; else if (k2 < 0) k2 = pm; else if (k3 < 0) k3 = pm; } }
;     const int tid = threadIdx.x;
;     LAS float* tab = (LAS float*)(lds + RS_TAB_OFF); LAS int* keys = (LAS int*)(lds + RS_KEY_OFF);
;     if (tid < 256) {
;         if (k0 >= 0) tab[tid] = rs[k0 * 256 + tid];
;         if (k1 >= 0) tab[256 + tid] = rs[k1 * 256 + tid];
;         if (k2 >= 0) tab[512 + tid] = rs[k2 * 256 + tid];
;         if (k3 >= 0) tab[768 + tid] = rs[k3 * 256 + tid];
;     }
;     if (tid == 0) { keys[0] = k0; keys[1] = k1; keys[2] = k2; keys[3] = k3; }
;     __syncthreads();
; }
; template <bool SRC_F32, bool FINAL, int R> __device__ __forceinline__ void ew_compute(const EwSet<SRC_F32, R>& S, int rb, const f32x4 (&g)[4], bf16* hb_out, float* out32, float scale, float* rs_out, int lane) {
;     ...
;         if (!FINAL) { const float tot = wave_sum(s2); if (lane == 0) rs_out[rb + i] = 1.0f / sqrtf(tot * (1.f / D) + EPS); }
.LBB0_1051:
	s_movk_i32 s0, 0x100
	v_cmp_gt_u32_e32 vcc, s0, v195
	s_and_saveexec_b64 s[0:1], vcc
	s_cbranch_execz .LBB0_1060
	s_add_u32 s80, s28, 0x4c00000
	s_addc_u32 s81, s29, 0
	s_cmp_lt_i32 s10, 0
	s_cbranch_scc1 .Lhp1_l0
	v_lshl_or_b32 v0, s10, 8, v195
	v_lshlrev_b32_e32 v2, 6, v0
	global_load_dwordx4 v[4:7], v2, s[80:81]
	global_load_dwordx4 v[8:11], v2, s[80:81] offset:16
	global_load_dwordx4 v[12:15], v2, s[80:81] offset:32
	global_load_dwordx4 v[16:19], v2, s[80:81] offset:48
.Lhp1_l0:
	s_cmp_lt_i32 s11, 0
	s_cbranch_scc1 .Lhp1_l1
	v_lshl_or_b32 v0, s11, 8, v195
	v_lshlrev_b32_e32 v2, 6, v0
	global_load_dwordx4 v[20:23], v2, s[80:81]
	global_load_dwordx4 v[24:27], v2, s[80:81] offset:16
	global_load_dwordx4 v[28:31], v2, s[80:81] offset:32
	global_load_dwordx4 v[32:35], v2, s[80:81] offset:48
.Lhp1_l1:
	s_cmp_lt_i32 s22, 0
	s_cbranch_scc1 .Lhp1_l2
	v_lshl_or_b32 v0, s22, 8, v195
	v_lshlrev_b32_e32 v2, 6, v0
	global_load_dwordx4 v[36:39], v2, s[80:81]
	global_load_dwordx4 v[40:43], v2, s[80:81] offset:16
	global_load_dwordx4 v[44:47], v2, s[80:81] offset:32
	global_load_dwordx4 v[48:51], v2, s[80:81] offset:48
.Lhp1_l2:
	s_cmp_lt_i32 s8, 0
	s_cbranch_scc1 .Lhp1_l3
	v_lshl_or_b32 v0, s8, 8, v195
	v_lshlrev_b32_e32 v2, 6, v0
	global_load_dwordx4 v[52:55], v2, s[80:81]
	global_load_dwordx4 v[56:59], v2, s[80:81] offset:16
	global_load_dwordx4 v[60:63], v2, s[80:81] offset:32
	global_load_dwordx4 v[64:67], v2, s[80:81] offset:48
.Lhp1_l3:
	s_waitcnt vmcnt(0)
	s_cmp_lt_i32 s10, 0
	s_cbranch_scc1 .Lhp1_c0
	v_lshl_or_b32 v0, s10, 8, v195
	v_lshlrev_b32_e32 v3, 2, v0
	v_lshl_add_u32 v1, v195, 2, 0
	v_add_u32_e32 v1, 0x20000, v1
	v_add_f32_e32 v0, v4, v5
	v_add_f32_e32 v0, v6, v0
	v_add_f32_e32 v0, v7, v0
	v_add_f32_e32 v0, v8, v0
	v_add_f32_e32 v0, v9, v0
	v_add_f32_e32 v0, v10, v0
	v_add_f32_e32 v0, v11, v0
	v_add_f32_e32 v0, v12, v0
	v_add_f32_e32 v0, v13, v0
	v_add_f32_e32 v0, v14, v0
	v_add_f32_e32 v0, v15, v0
	v_add_f32_e32 v0, v16, v0
	v_add_f32_e32 v0, v17, v0
	v_add_f32_e32 v0, v18, v0
	v_add_f32_e32 v0, v19, v0
	v_mul_f32_e32 v0, 0x3a800000, v0
	v_add_f32_e32 v0, 0x358637bd, v0
	v_rsq_f32_e32 v0, v0
	s_nop 0
	global_store_dword v3, v0, s[92:93]
	ds_write_b32 v1, v0
.Lhp1_c0:
	s_cmp_lt_i32 s11, 0
	s_cbranch_scc1 .Lhp1_c1
	v_lshl_or_b32 v0, s11, 8, v195
	v_lshlrev_b32_e32 v3, 2, v0
	s_add_i32 s4, 0, 0x20000
	v_lshl_add_u32 v1, v195, 2, 0
	v_add_u32_e32 v1, 0x20000, v1
	v_add_f32_e32 v0, v20, v21
	v_add_f32_e32 v0, v22, v0
	v_add_f32_e32 v0, v23, v0
	v_add_f32_e32 v0, v24, v0
	v_add_f32_e32 v0, v25, v0
	v_add_f32_e32 v0, v26, v0
	v_add_f32_e32 v0, v27, v0
	v_add_f32_e32 v0, v28, v0
	v_add_f32_e32 v0, v29, v0
	v_add_f32_e32 v0, v30, v0
	v_add_f32_e32 v0, v31, v0
	v_add_f32_e32 v0, v32, v0
	v_add_f32_e32 v0, v33, v0
	v_add_f32_e32 v0, v34, v0
	v_add_f32_e32 v0, v35, v0
	v_mul_f32_e32 v0, 0x3a800000, v0
	v_add_f32_e32 v0, 0x358637bd, v0
	v_rsq_f32_e32 v0, v0
	s_nop 0
	global_store_dword v3, v0, s[92:93]
	ds_write_b32 v1, v0 offset:1024
.Lhp1_c1:
	s_cmp_lt_i32 s22, 0
	s_cbranch_scc1 .Lhp1_c2
	v_lshl_or_b32 v0, s22, 8, v195
	v_lshlrev_b32_e32 v3, 2, v0
	s_add_i32 s4, 0, 0x20000
	v_lshl_add_u32 v1, v195, 2, 0
	v_add_u32_e32 v1, 0x20000, v1
	v_add_f32_e32 v0, v36, v37
	v_add_f32_e32 v0, v38, v0
	v_add_f32_e32 v0, v39, v0
	v_add_f32_e32 v0, v40, v0
	v_add_f32_e32 v0, v41, v0
	v_add_f32_e32 v0, v42, v0
	v_add_f32_e32 v0, v43, v0
	v_add_f32_e32 v0, v44, v0
	v_add_f32_e32 v0, v45, v0
	v_add_f32_e32 v0, v46, v0
	v_add_f32_e32 v0, v47, v0
	v_add_f32_e32 v0, v48, v0
	v_add_f32_e32 v0, v49, v0
	v_add_f32_e32 v0, v50, v0
	v_add_f32_e32 v0, v51, v0
	v_mul_f32_e32 v0, 0x3a800000, v0
	v_add_f32_e32 v0, 0x358637bd, v0
	v_rsq_f32_e32 v0, v0
	s_nop 0
	global_store_dword v3, v0, s[92:93]
	ds_write_b32 v1, v0 offset:2048
.Lhp1_c2:
	s_cmp_lt_i32 s8, 0
	s_cbranch_scc1 .Lhp1_c3
	v_lshl_or_b32 v0, s8, 8, v195
	v_lshlrev_b32_e32 v3, 2, v0
	s_add_i32 s4, 0, 0x20000
	v_lshl_add_u32 v1, v195, 2, 0
	v_add_u32_e32 v1, 0x20000, v1
	v_add_f32_e32 v0, v52, v53
	v_add_f32_e32 v0, v54, v0
	v_add_f32_e32 v0, v55, v0
	v_add_f32_e32 v0, v56, v0
	v_add_f32_e32 v0, v57, v0
	v_add_f32_e32 v0, v58, v0
	v_add_f32_e32 v0, v59, v0
	v_add_f32_e32 v0, v60, v0
	v_add_f32_e32 v0, v61, v0
	v_add_f32_e32 v0, v62, v0
	v_add_f32_e32 v0, v63, v0
	v_add_f32_e32 v0, v64, v0
	v_add_f32_e32 v0, v65, v0
	v_add_f32_e32 v0, v66, v0
	v_add_f32_e32 v0, v67, v0
	v_mul_f32_e32 v0, 0x3a800000, v0
	v_add_f32_e32 v0, 0x358637bd, v0
	v_rsq_f32_e32 v0, v0
	s_nop 0
	global_store_dword v3, v0, s[92:93]
	ds_write_b32 v1, v0 offset:3072
.Lhp1_c3:
.LBB0_1060:
	s_or_b64 exec, exec, s[0:1]
	v_cmp_eq_u32_e32 vcc, 0, v195
	s_and_saveexec_b64 s[0:1], vcc
	s_cbranch_execz .LBB0_1062
	s_add_i32 s4, 0, 0x21000
	v_mov_b32_e32 v0, s10
	v_mov_b32_e32 v1, s11
	v_mov_b32_e32 v2, s22
	v_mov_b32_e32 v3, s8
	v_mov_b32_e32 v4, s4
	ds_write_b128 v4, v[0:3]

; #define LAS __attribute__((address_space(3)))
; __device__ __forceinline__ void rs_table_fill(LAS unsigned char* lds, const pg8::StaticOrder& S, const float* rs) {
;     int k0 = -1, k1 = -1, k2 = -1, k3 = -1;
;     for (int i = 0;; ++i) { pg8::Unit u; if (!S.next(i, u)) break; const int pm = u.pm;
;         if (pm != k0 && pm != k1 && pm != k2 && pm != k3) { if (k0 < 0) k0 = pm; else if (k1 < 0) k1 = pm; else if (k2 < 0) k2 = pm; else if (k3 < 0) k3 = pm; } }
;     const int tid = threadIdx.x;
;     LAS float* tab = (LAS float*)(lds + RS_TAB_OFF); LAS int* keys = (LAS int*)(lds + RS_KEY_OFF);
;     if (tid < 256) {
;         if (k0 >= 0) tab[tid] = rs[k0 * 256 + tid];
;         if (k1 >= 0) tab[256 + tid] = rs[k1 * 256 + tid];
;         if (k2 >= 0) tab[512 + tid] = rs[k2 * 256 + tid];
;         if (k3 >= 0) tab[768 + tid] = rs[k3 * 256 + tid];
;     }
;     if (tid == 0) { keys[0] = k0; keys[1] = k1; keys[2] = k2; keys[3] = k3; }
;     __syncthreads();
; }
.LBB0_1325:
	s_movk_i32 s0, 0x100
	v_cmp_gt_u32_e32 vcc, s0, v195
	s_and_saveexec_b64 s[0:1], vcc
	s_cbranch_execz .LBB0_1334
	s_add_u32 s80, s28, 0x4c00000
	s_addc_u32 s81, s29, 0
	s_cmp_lt_i32 s8, 0
	s_cbranch_scc1 .Lhp2_l0
	v_lshl_or_b32 v0, s8, 8, v195
	v_lshlrev_b32_e32 v2, 6, v0
	global_load_dwordx4 v[4:7], v2, s[80:81]
	global_load_dwordx4 v[8:11], v2, s[80:81] offset:16
	global_load_dwordx4 v[12:15], v2, s[80:81] offset:32
	global_load_dwordx4 v[16:19], v2, s[80:81] offset:48
.Lhp2_l0:
	s_cmp_lt_i32 s9, 0
	s_cbranch_scc1 .Lhp2_l1
	v_lshl_or_b32 v0, s9, 8, v195
	v_lshlrev_b32_e32 v2, 6, v0
	global_load_dwordx4 v[20:23], v2, s[80:81]
	global_load_dwordx4 v[24:27], v2, s[80:81] offset:16
	global_load_dwordx4 v[28:31], v2, s[80:81] offset:32
	global_load_dwordx4 v[32:35], v2, s[80:81] offset:48
.Lhp2_l1:
	s_cmp_lt_i32 s14, 0
	s_cbranch_scc1 .Lhp2_l2
	v_lshl_or_b32 v0, s14, 8, v195
	v_lshlrev_b32_e32 v2, 6, v0
	global_load_dwordx4 v[36:39], v2, s[80:81]
	global_load_dwordx4 v[40:43], v2, s[80:81] offset:16
	global_load_dwordx4 v[44:47], v2, s[80:81] offset:32
	global_load_dwordx4 v[48:51], v2, s[80:81] offset:48

; #define LAS __attribute__((address_space(3)))
; __device__ __forceinline__ void rs_table_fill(LAS unsigned char* lds, const pg8::StaticOrder& S, const float* rs) {
;     int k0 = -1, k1 = -1, k2 = -1, k3 = -1;
;     for (int i = 0;; ++i) { pg8::Unit u; if (!S.next(i, u)) break; const int pm = u.pm;
;         if (pm != k0 && pm != k1 && pm != k2 && pm != k3) { if (k0 < 0) k0 = pm; else if (k1 < 0) k1 = pm; else if (k2 < 0) k2 = pm; else if (k3 < 0) k3 = pm; } }
;     const int tid = threadIdx.x;
;     LAS float* tab = (LAS float*)(lds + RS_TAB_OFF); LAS int* keys = (LAS int*)(lds + RS_KEY_OFF);
;     if (tid < 256) {
;         if (k0 >= 0) tab[tid] = rs[k0 * 256 + tid];
;         if (k1 >= 0) tab[256 + tid] = rs[k1 * 256 + tid];
;         if (k2 >= 0) tab[512 + tid] = rs[k2 * 256 + tid];
;         if (k3 >= 0) tab[768 + tid] = rs[k3 * 256 + tid];
;     }
;     if (tid == 0) { keys[0] = k0; keys[1] = k1; keys[2] = k2; keys[3] = k3; }
;     __syncthreads();
; }
; template <bool SRC_F32, bool FINAL, int R> __device__ __forceinline__ void ew_compute(const EwSet<SRC_F32, R>& S, int rb, const f32x4 (&g)[4], bf16* hb_out, float* out32, float scale, float* rs_out, int lane) {
;     ...
;         if (!FINAL) { const float tot = wave_sum(s2); if (lane == 0) rs_out[rb + i] = 1.0f / sqrtf(tot * (1.f / D) + EPS); }
.Lhp2_l3:
	s_waitcnt vmcnt(0)
	s_cmp_lt_i32 s8, 0
	s_cbranch_scc1 .Lhp2_c0
	v_lshl_or_b32 v0, s8, 8, v195
	v_lshlrev_b32_e32 v3, 2, v0
	v_lshl_add_u32 v1, v195, 2, 0
	v_add_u32_e32 v1, 0x20000, v1
	v_add_f32_e32 v0, v4, v5
	v_add_f32_e32 v0, v6, v0
	v_add_f32_e32 v0, v7, v0
	v_add_f32_e32 v0, v8, v0
	v_add_f32_e32 v0, v9, v0
	v_add_f32_e32 v0, v10, v0
	v_add_f32_e32 v0, v11, v0
	v_add_f32_e32 v0, v12, v0
	v_add_f32_e32 v0, v13, v0
	v_add_f32_e32 v0, v14, v0
	v_add_f32_e32 v0, v15, v0
	v_add_f32_e32 v0, v16, v0
	v_add_f32_e32 v0, v17, v0
	v_add_f32_e32 v0, v18, v0
	v_add_f32_e32 v0, v19, v0
	v_mul_f32_e32 v0, 0x3a800000, v0
	v_add_f32_e32 v0, 0x358637bd, v0
	v_rsq_f32_e32 v0, v0
	s_nop 0
	global_store_dword v3, v0, s[92:93]
	ds_write_b32 v1, v0
.Lhp2_c0:
	s_cmp_lt_i32 s9, 0
	s_cbranch_scc1 .Lhp2_c1
	v_lshl_or_b32 v0, s9, 8, v195
	v_lshlrev_b32_e32 v3, 2, v0
	s_add_i32 s4, 0, 0x20000
	v_lshl_add_u32 v1, v195, 2, 0
	v_add_u32_e32 v1, 0x20000, v1
	v_add_f32_e32 v0, v20, v21
	v_add_f32_e32 v0, v22, v0
	v_add_f32_e32 v0, v23, v0
	v_add_f32_e32 v0, v24, v0
	v_add_f32_e32 v0, v25, v0
	v_add_f32_e32 v0, v26, v0
	v_add_f32_e32 v0, v27, v0
	v_add_f32_e32 v0, v28, v0
	v_add_f32_e32 v0, v29, v0
	v_add_f32_e32 v0, v30, v0
	v_add_f32_e32 v0, v31, v0
	v_add_f32_e32 v0, v32, v0
	v_add_f32_e32 v0, v33, v0
	v_add_f32_e32 v0, v34, v0
	v_add_f32_e32 v0, v35, v0
	v_mul_f32_e32 v0, 0x3a800000, v0
	v_add_f32_e32 v0, 0x358637bd, v0
	v_rsq_f32_e32 v0, v0
	s_nop 0
	global_store_dword v3, v0, s[92:93]
	ds_write_b32 v1, v0 offset:1024
.Lhp2_c1:
	s_cmp_lt_i32 s14, 0
	s_cbranch_scc1 .Lhp2_c2
	v_lshl_or_b32 v0, s14, 8, v195
	v_lshlrev_b32_e32 v3, 2, v0
	s_add_i32 s4, 0, 0x20000
	v_lshl_add_u32 v1, v195, 2, 0
	v_add_u32_e32 v1, 0x20000, v1
	v_add_f32_e32 v0, v36, v37
	v_add_f32_e32 v0, v38, v0
	v_add_f32_e32 v0, v39, v0
	v_add_f32_e32 v0, v40, v0
	v_add_f32_e32 v0, v41, v0
	v_add_f32_e32 v0, v42, v0
	v_add_f32_e32 v0, v43, v0
	v_add_f32_e32 v0, v44, v0
	v_add_f32_e32 v0, v45, v0
	v_add_f32_e32 v0, v46, v0
	v_add_f32_e32 v0, v47, v0
	v_add_f32_e32 v0, v48, v0
	v_add_f32_e32 v0, v49, v0
	v_add_f32_e32 v0, v50, v0
	v_add_f32_e32 v0, v51, v0
	v_mul_f32_e32 v0, 0x3a800000, v0
	v_add_f32_e32 v0, 0x358637bd, v0
	v_rsq_f32_e32 v0, v0
	s_nop 0
	global_store_dword v3, v0, s[92:93]
	ds_write_b32 v1, v0 offset:2048

; __device__ __forceinline__ void rs_table_fill(LAS unsigned char* lds, const pg8::StaticOrder& S, const float* rs) {
;     ...
;     if (tid == 0) { keys[0] = k0; keys[1] = k1; keys[2] = k2; keys[3] = k3; }
;     __syncthreads();
.Lhp2_c3:
.LBB0_1334:
	s_or_b64 exec, exec, s[0:1]
	v_cmp_eq_u32_e32 vcc, 0, v195
	s_and_saveexec_b64 s[0:1], vcc
	s_cbranch_execz .LBB0_1336
	s_add_i32 s4, 0, 0x21000
	v_mov_b32_e32 v0, s8
	v_mov_b32_e32 v1, s9
	v_mov_b32_e32 v2, s14
	v_mov_b32_e32 v3, s6
	v_mov_b32_e32 v4, s4
	ds_write_b128 v4, v[0:3]
